# opt23: full stack = opt19 + G6 EpiResid pipelined + G8 phase-A pair prefetch + next-unit K/V L2 prefetch
# baseline (speedup 1.0000x reference)
; __device__ __forceinline__ unsigned cvt_pk_bf16(float lo, float hi) { f32x2_t v = {lo, hi}; bf16x2_t b = __builtin_convertvector(v, bf16x2_t); return __builtin_bit_cast(unsigned, b); }
;     __device__ __forceinline__ void operator()(const Acc& acc, const Unit& u, int wr, int wc, int fr, int fq) const {
;         const int row0 = u.pm * BM + wr * 64 + fr, col0 = u.pn * BM + wc * 32 + 8 * fq;
; #pragma unroll
;         for (int ai = 0; ai < 2; ++ai)
; #pragma unroll
;             for (int m = 0; m < 4; ++m) {
;                 const int row = row0 + ai * HALF + m * 16; float sq = 0.f;
; #pragma unroll
;                 for (int bj = 0; bj < 2; ++bj) {
;                     const size_t off = (size_t)row * DM + col0 + bj * HALF;
;                     const f32x4 b0 = *(const f32x4*)(base + off), b1 = *(const f32x4*)(base + off + 4);
;                     const f32x4 x0 = b0 + acc[ai][bj][m][0] * alpha, x1 = b1 + acc[ai][bj][m][1] * alpha;
;                     __builtin_nontemporal_store(x0, (f32x4*)(out + off)); __builtin_nontemporal_store(x1, (f32x4*)(out + off + 4));
;                     sq += (x0[0] * x0[0] + x0[1] * x0[1]) + (x0[2] * x0[2] + x0[3] * x0[3]) + (x1[0] * x1[0] + x1[1] * x1[1]) + (x1[2] * x1[2] + x1[3] * x1[3]);
;                     if (xb) { u32x4 w; w.x = cvt_pk_bf16(x0[0], x0[1]); w.y = cvt_pk_bf16(x0[2], x0[3]); w.z = cvt_pk_bf16(x1[0], x1[1]); w.w = cvt_pk_bf16(x1[2], x1[3]); *(u32x4*)(xb + off) = w; }
;                 }
;                 sq += __shfl_xor(sq, 16); sq += __shfl_xor(sq, 32);
;                 if (fq == 0) unsafeAtomicAdd(ss + row, sq);
;             }
.LBB0_1237:
	s_and_b64 vcc, exec, s[36:37]
	s_cbranch_vccz .Lg6_epi_old
	v_lshl_add_u32 v146, s12, 8, v152
	v_lshl_or_b32 v144, s46, 8, v154
	v_lshl_add_u32 v145, v146, 10, v144
	v_lshlrev_b32_e32 v144, 2, v145
	v_lshlrev_b32_e32 v145, 1, v145
	v_lshlrev_b32_e32 v146, 2, v146
	v_mbcnt_lo_u32_b32 v149, -1, 0
	v_mbcnt_hi_u32_b32 v149, -1, v149
	v_xor_b32_e32 v147, 16, v149
	v_lshlrev_b32_e32 v147, 2, v147
	v_xor_b32_e32 v148, 32, v149
	v_lshlrev_b32_e32 v148, 2, v148
	s_mov_b64 s[84:85], s[82:83]
	global_load_dwordx4 v[184:187], v144, s[84:85]
	global_load_dwordx4 v[188:191], v144, s[84:85] offset:16
	global_load_dwordx4 v[192:195], v144, s[84:85] offset:512
	global_load_dwordx4 v[196:199], v144, s[84:85] offset:528
	s_add_u32 s84, s82, 0x10000
	s_addc_u32 s85, s83, 0
	global_load_dwordx4 v[200:203], v144, s[84:85]
	global_load_dwordx4 v[204:207], v144, s[84:85] offset:16
	global_load_dwordx4 v[208:211], v144, s[84:85] offset:512
	global_load_dwordx4 v[212:215], v144, s[84:85] offset:528
	s_waitcnt vmcnt(4)
	v_fma_f32 v124, v124, 1.0, v184
	v_fma_f32 v125, v125, 1.0, v185
	v_fma_f32 v126, v126, 1.0, v186
	v_fma_f32 v127, v127, 1.0, v187
	v_fma_f32 v120, v120, 1.0, v188
	v_fma_f32 v121, v121, 1.0, v189
	v_fma_f32 v122, v122, 1.0, v190
	v_fma_f32 v123, v123, 1.0, v191
	v_fma_f32 v116, v116, 1.0, v192
	v_fma_f32 v117, v117, 1.0, v193
	v_fma_f32 v118, v118, 1.0, v194
	v_fma_f32 v119, v119, 1.0, v195
	v_fma_f32 v112, v112, 1.0, v196
	v_fma_f32 v113, v113, 1.0, v197
	v_fma_f32 v114, v114, 1.0, v198
	v_fma_f32 v115, v115, 1.0, v199
	s_add_u32 s84, s82, 0x20000
	s_addc_u32 s85, s83, 0
	global_load_dwordx4 v[216:219], v144, s[84:85]
	global_load_dwordx4 v[220:223], v144, s[84:85] offset:16
	global_load_dwordx4 v[224:227], v144, s[84:85] offset:512
	global_load_dwordx4 v[228:231], v144, s[84:85] offset:528
	s_mov_b64 s[86:87], s[82:83]
	global_store_dwordx4 v144, v[124:127], s[86:87] nt
	global_store_dwordx4 v144, v[120:123], s[86:87] offset:16 nt
	global_store_dwordx4 v144, v[116:119], s[86:87] offset:512 nt
	global_store_dwordx4 v144, v[112:115], s[86:87] offset:528 nt
	v_cvt_pk_bf16_f32 v236, v124, v125
	v_cvt_pk_bf16_f32 v237, v126, v127
	v_cvt_pk_bf16_f32 v238, v120, v121
	v_cvt_pk_bf16_f32 v239, v122, v123
	v_cvt_pk_bf16_f32 v240, v116, v117
	v_cvt_pk_bf16_f32 v241, v118, v119
	v_cvt_pk_bf16_f32 v242, v112, v113
	v_cvt_pk_bf16_f32 v243, v114, v115
	s_mov_b64 s[88:89], s[72:73]
	global_store_dwordx4 v145, v[236:239], s[88:89]
	global_store_dwordx4 v145, v[240:243], s[88:89] offset:256
	v_mul_f32_e32 v232, v125, v125
	v_fmac_f32_e32 v232, v124, v124
	v_mul_f32_e32 v233, v121, v121
	v_fmac_f32_e32 v233, v120, v120
	v_mul_f32_e32 v234, v117, v117
	v_fmac_f32_e32 v234, v116, v116
	v_mul_f32_e32 v235, v113, v113
	v_fmac_f32_e32 v235, v112, v112
	v_mul_f32_e32 v248, v127, v127
	v_fmac_f32_e32 v248, v126, v126
	v_mul_f32_e32 v249, v123, v123
	v_fmac_f32_e32 v249, v122, v122
	v_mul_f32_e32 v250, v119, v119
	v_fmac_f32_e32 v250, v118, v118
	v_mul_f32_e32 v251, v115, v115
	v_fmac_f32_e32 v251, v114, v114
	v_add_f32_e32 v232, v232, v248
	v_add_f32_e32 v233, v233, v249
	v_add_f32_e32 v234, v234, v250
	v_add_f32_e32 v235, v235, v251
	v_add_f32_e32 v232, v232, v233
	v_add_f32_e32 v234, v234, v235
	v_add_f32_e32 v232, v232, v234
	ds_bpermute_b32 v233, v147, v232
	s_waitcnt lgkmcnt(0)
	v_add_f32_e32 v232, v232, v233
	ds_bpermute_b32 v233, v148, v232
	s_waitcnt lgkmcnt(0)
	v_add_f32_e32 v232, v232, v233
	s_and_saveexec_b64 s[6:7], s[8:9]
	s_nop 1
	global_atomic_add_f32 v146, v232, s[2:3]
	s_mov_b64 exec, s[6:7]
	s_waitcnt vmcnt(11)
	v_fma_f32 v108, v108, 1.0, v200
	v_fma_f32 v109, v109, 1.0, v201
	v_fma_f32 v110, v110, 1.0, v202
	v_fma_f32 v111, v111, 1.0, v203
	v_fma_f32 v104, v104, 1.0, v204
	v_fma_f32 v105, v105, 1.0, v205
	v_fma_f32 v106, v106, 1.0, v206
	v_fma_f32 v107, v107, 1.0, v207
	v_fma_f32 v100, v100, 1.0, v208
	v_fma_f32 v101, v101, 1.0, v209
	v_fma_f32 v102, v102, 1.0, v210
	v_fma_f32 v103, v103, 1.0, v211
	v_fma_f32 v96, v96, 1.0, v212
	v_fma_f32 v97, v97, 1.0, v213
	v_fma_f32 v98, v98, 1.0, v214
	v_fma_f32 v99, v99, 1.0, v215
	s_add_u32 s84, s82, 0x30000
	s_addc_u32 s85, s83, 0
	global_load_dwordx4 v[184:187], v144, s[84:85]
	global_load_dwordx4 v[188:191], v144, s[84:85] offset:16
	global_load_dwordx4 v[192:195], v144, s[84:85] offset:512
	global_load_dwordx4 v[196:199], v144, s[84:85] offset:528
	s_add_u32 s86, s82, 0x10000
	s_addc_u32 s87, s83, 0
	global_store_dwordx4 v144, v[108:111], s[86:87] nt
	global_store_dwordx4 v144, v[104:107], s[86:87] offset:16 nt
	global_store_dwordx4 v144, v[100:103], s[86:87] offset:512 nt
	global_store_dwordx4 v144, v[96:99], s[86:87] offset:528 nt
	v_cvt_pk_bf16_f32 v236, v108, v109
	v_cvt_pk_bf16_f32 v237, v110, v111
	v_cvt_pk_bf16_f32 v238, v104, v105
	v_cvt_pk_bf16_f32 v239, v106, v107
	v_cvt_pk_bf16_f32 v240, v100, v101
	v_cvt_pk_bf16_f32 v241, v102, v103
	v_cvt_pk_bf16_f32 v242, v96, v97
	v_cvt_pk_bf16_f32 v243, v98, v99
	s_add_u32 s88, s72, 0x8000
	s_addc_u32 s89, s73, 0
	global_store_dwordx4 v145, v[236:239], s[88:89]
	global_store_dwordx4 v145, v[240:243], s[88:89] offset:256
	v_mul_f32_e32 v232, v109, v109
	v_fmac_f32_e32 v232, v108, v108
	v_mul_f32_e32 v233, v105, v105
	v_fmac_f32_e32 v233, v104, v104
	v_mul_f32_e32 v234, v101, v101
	v_fmac_f32_e32 v234, v100, v100
	v_mul_f32_e32 v235, v97, v97
	v_fmac_f32_e32 v235, v96, v96
	v_mul_f32_e32 v248, v111, v111
	v_fmac_f32_e32 v248, v110, v110
	v_mul_f32_e32 v249, v107, v107
	v_fmac_f32_e32 v249, v106, v106
	v_mul_f32_e32 v250, v103, v103
	v_fmac_f32_e32 v250, v102, v102
	v_mul_f32_e32 v251, v99, v99
	v_fmac_f32_e32 v251, v98, v98
	v_add_f32_e32 v232, v232, v248
	v_add_f32_e32 v233, v233, v249
	v_add_f32_e32 v234, v234, v250
	v_add_f32_e32 v235, v235, v251
	v_add_f32_e32 v232, v232, v233
	v_add_f32_e32 v234, v234, v235
	v_add_f32_e32 v232, v232, v234
	ds_bpermute_b32 v233, v147, v232
	s_waitcnt lgkmcnt(0)
; __device__ __forceinline__ unsigned cvt_pk_bf16(float lo, float hi) { f32x2_t v = {lo, hi}; bf16x2_t b = __builtin_convertvector(v, bf16x2_t); return __builtin_bit_cast(unsigned, b); }
;     __device__ __forceinline__ void operator()(const Acc& acc, const Unit& u, int wr, int wc, int fr, int fq) const {
;         const int row0 = u.pm * BM + wr * 64 + fr, col0 = u.pn * BM + wc * 32 + 8 * fq;
; #pragma unroll
;         for (int ai = 0; ai < 2; ++ai)
; #pragma unroll
;             for (int m = 0; m < 4; ++m) {
;                 const int row = row0 + ai * HALF + m * 16; float sq = 0.f;
; #pragma unroll
;                 for (int bj = 0; bj < 2; ++bj) {
;                     const size_t off = (size_t)row * DM + col0 + bj * HALF;
;                     const f32x4 b0 = *(const f32x4*)(base + off), b1 = *(const f32x4*)(base + off + 4);
;                     const f32x4 x0 = b0 + acc[ai][bj][m][0] * alpha, x1 = b1 + acc[ai][bj][m][1] * alpha;
;                     __builtin_nontemporal_store(x0, (f32x4*)(out + off)); __builtin_nontemporal_store(x1, (f32x4*)(out + off + 4));
;                     sq += (x0[0] * x0[0] + x0[1] * x0[1]) + (x0[2] * x0[2] + x0[3] * x0[3]) + (x1[0] * x1[0] + x1[1] * x1[1]) + (x1[2] * x1[2] + x1[3] * x1[3]);
;                     if (xb) { u32x4 w; w.x = cvt_pk_bf16(x0[0], x0[1]); w.y = cvt_pk_bf16(x0[2], x0[3]); w.z = cvt_pk_bf16(x1[0], x1[1]); w.w = cvt_pk_bf16(x1[2], x1[3]); *(u32x4*)(xb + off) = w; }
;                 }
;                 sq += __shfl_xor(sq, 16); sq += __shfl_xor(sq, 32);
;                 if (fq == 0) unsafeAtomicAdd(ss + row, sq);
;             }
	v_add_f32_e32 v232, v232, v233
	ds_bpermute_b32 v233, v148, v232
	s_waitcnt lgkmcnt(0)
	v_add_f32_e32 v232, v232, v233
	s_and_saveexec_b64 s[6:7], s[8:9]
	s_nop 1
	global_atomic_add_f32 v146, v232, s[2:3] offset:64
	s_mov_b64 exec, s[6:7]
	s_waitcnt vmcnt(18)
	v_fma_f32 v92, v92, 1.0, v216
	v_fma_f32 v93, v93, 1.0, v217
	v_fma_f32 v94, v94, 1.0, v218
	v_fma_f32 v95, v95, 1.0, v219
	v_fma_f32 v88, v88, 1.0, v220
	v_fma_f32 v89, v89, 1.0, v221
	v_fma_f32 v90, v90, 1.0, v222
	v_fma_f32 v91, v91, 1.0, v223
	v_fma_f32 v84, v84, 1.0, v224
	v_fma_f32 v85, v85, 1.0, v225
	v_fma_f32 v86, v86, 1.0, v226
	v_fma_f32 v87, v87, 1.0, v227
	v_fma_f32 v80, v80, 1.0, v228
	v_fma_f32 v81, v81, 1.0, v229
	v_fma_f32 v82, v82, 1.0, v230
	v_fma_f32 v83, v83, 1.0, v231
	s_add_u32 s84, s82, 0x80000
	s_addc_u32 s85, s83, 0
	global_load_dwordx4 v[200:203], v144, s[84:85]
	global_load_dwordx4 v[204:207], v144, s[84:85] offset:16
	global_load_dwordx4 v[208:211], v144, s[84:85] offset:512
	global_load_dwordx4 v[212:215], v144, s[84:85] offset:528
	s_add_u32 s86, s82, 0x20000
	s_addc_u32 s87, s83, 0
	global_store_dwordx4 v144, v[92:95], s[86:87] nt
	global_store_dwordx4 v144, v[88:91], s[86:87] offset:16 nt
	global_store_dwordx4 v144, v[84:87], s[86:87] offset:512 nt
	global_store_dwordx4 v144, v[80:83], s[86:87] offset:528 nt
	v_cvt_pk_bf16_f32 v236, v92, v93
	v_cvt_pk_bf16_f32 v237, v94, v95
	v_cvt_pk_bf16_f32 v238, v88, v89
	v_cvt_pk_bf16_f32 v239, v90, v91
	v_cvt_pk_bf16_f32 v240, v84, v85
	v_cvt_pk_bf16_f32 v241, v86, v87
	v_cvt_pk_bf16_f32 v242, v80, v81
	v_cvt_pk_bf16_f32 v243, v82, v83
	s_add_u32 s88, s72, 0x10000
	s_addc_u32 s89, s73, 0
	global_store_dwordx4 v145, v[236:239], s[88:89]
	global_store_dwordx4 v145, v[240:243], s[88:89] offset:256
	v_mul_f32_e32 v232, v93, v93
	v_fmac_f32_e32 v232, v92, v92
	v_mul_f32_e32 v233, v89, v89
	v_fmac_f32_e32 v233, v88, v88
	v_mul_f32_e32 v234, v85, v85
	v_fmac_f32_e32 v234, v84, v84
	v_mul_f32_e32 v235, v81, v81
	v_fmac_f32_e32 v235, v80, v80
	v_mul_f32_e32 v248, v95, v95
	v_fmac_f32_e32 v248, v94, v94
	v_mul_f32_e32 v249, v91, v91
	v_fmac_f32_e32 v249, v90, v90
	v_mul_f32_e32 v250, v87, v87
	v_fmac_f32_e32 v250, v86, v86
	v_mul_f32_e32 v251, v83, v83
	v_fmac_f32_e32 v251, v82, v82
	v_add_f32_e32 v232, v232, v248
	v_add_f32_e32 v233, v233, v249
	v_add_f32_e32 v234, v234, v250
	v_add_f32_e32 v235, v235, v251
	v_add_f32_e32 v232, v232, v233
	v_add_f32_e32 v234, v234, v235
	v_add_f32_e32 v232, v232, v234
	ds_bpermute_b32 v233, v147, v232
	s_waitcnt lgkmcnt(0)
	v_add_f32_e32 v232, v232, v233
	ds_bpermute_b32 v233, v148, v232
	s_waitcnt lgkmcnt(0)
	v_add_f32_e32 v232, v232, v233
	s_and_saveexec_b64 s[6:7], s[8:9]
	s_nop 1
	global_atomic_add_f32 v146, v232, s[2:3] offset:128
	s_mov_b64 exec, s[6:7]
	s_waitcnt vmcnt(18)
	v_fma_f32 v76, v76, 1.0, v184
	v_fma_f32 v77, v77, 1.0, v185
	v_fma_f32 v78, v78, 1.0, v186
	v_fma_f32 v79, v79, 1.0, v187
	v_fma_f32 v72, v72, 1.0, v188
	v_fma_f32 v73, v73, 1.0, v189
	v_fma_f32 v74, v74, 1.0, v190
	v_fma_f32 v75, v75, 1.0, v191
	v_fma_f32 v68, v68, 1.0, v192
	v_fma_f32 v69, v69, 1.0, v193
	v_fma_f32 v70, v70, 1.0, v194
	v_fma_f32 v71, v71, 1.0, v195
	v_fma_f32 v64, v64, 1.0, v196
	v_fma_f32 v65, v65, 1.0, v197
	v_fma_f32 v66, v66, 1.0, v198
	v_fma_f32 v67, v67, 1.0, v199
	s_add_u32 s84, s82, 0x90000
	s_addc_u32 s85, s83, 0
	global_load_dwordx4 v[216:219], v144, s[84:85]
	global_load_dwordx4 v[220:223], v144, s[84:85] offset:16
	global_load_dwordx4 v[224:227], v144, s[84:85] offset:512
	global_load_dwordx4 v[228:231], v144, s[84:85] offset:528
	s_add_u32 s86, s82, 0x30000
	s_addc_u32 s87, s83, 0
	global_store_dwordx4 v144, v[76:79], s[86:87] nt
	global_store_dwordx4 v144, v[72:75], s[86:87] offset:16 nt
	global_store_dwordx4 v144, v[68:71], s[86:87] offset:512 nt
	global_store_dwordx4 v144, v[64:67], s[86:87] offset:528 nt
	v_cvt_pk_bf16_f32 v236, v76, v77
	v_cvt_pk_bf16_f32 v237, v78, v79
	v_cvt_pk_bf16_f32 v238, v72, v73
	v_cvt_pk_bf16_f32 v239, v74, v75
	v_cvt_pk_bf16_f32 v240, v68, v69
	v_cvt_pk_bf16_f32 v241, v70, v71
	v_cvt_pk_bf16_f32 v242, v64, v65
	v_cvt_pk_bf16_f32 v243, v66, v67
	s_add_u32 s88, s72, 0x18000
	s_addc_u32 s89, s73, 0
	global_store_dwordx4 v145, v[236:239], s[88:89]
	global_store_dwordx4 v145, v[240:243], s[88:89] offset:256
	v_mul_f32_e32 v232, v77, v77
	v_fmac_f32_e32 v232, v76, v76
	v_mul_f32_e32 v233, v73, v73
	v_fmac_f32_e32 v233, v72, v72
	v_mul_f32_e32 v234, v69, v69
	v_fmac_f32_e32 v234, v68, v68
	v_mul_f32_e32 v235, v65, v65
	v_fmac_f32_e32 v235, v64, v64
	v_mul_f32_e32 v248, v79, v79
	v_fmac_f32_e32 v248, v78, v78
	v_mul_f32_e32 v249, v75, v75
	v_fmac_f32_e32 v249, v74, v74
	v_mul_f32_e32 v250, v71, v71
	v_fmac_f32_e32 v250, v70, v70
	v_mul_f32_e32 v251, v67, v67
	v_fmac_f32_e32 v251, v66, v66
	v_add_f32_e32 v232, v232, v248
	v_add_f32_e32 v233, v233, v249
	v_add_f32_e32 v234, v234, v250
	v_add_f32_e32 v235, v235, v251
	v_add_f32_e32 v232, v232, v233
	v_add_f32_e32 v234, v234, v235
	v_add_f32_e32 v232, v232, v234
	ds_bpermute_b32 v233, v147, v232
	s_waitcnt lgkmcnt(0)
	v_add_f32_e32 v232, v232, v233
	ds_bpermute_b32 v233, v148, v232
	s_waitcnt lgkmcnt(0)
	v_add_f32_e32 v232, v232, v233
	s_and_saveexec_b64 s[6:7], s[8:9]
	s_nop 1
	global_atomic_add_f32 v146, v232, s[2:3] offset:192
	s_mov_b64 exec, s[6:7]
	s_waitcnt vmcnt(18)
; __device__ __forceinline__ unsigned cvt_pk_bf16(float lo, float hi) { f32x2_t v = {lo, hi}; bf16x2_t b = __builtin_convertvector(v, bf16x2_t); return __builtin_bit_cast(unsigned, b); }
;     __device__ __forceinline__ void operator()(const Acc& acc, const Unit& u, int wr, int wc, int fr, int fq) const {
;         const int row0 = u.pm * BM + wr * 64 + fr, col0 = u.pn * BM + wc * 32 + 8 * fq;
; #pragma unroll
;         for (int ai = 0; ai < 2; ++ai)
; #pragma unroll
;             for (int m = 0; m < 4; ++m) {
;                 const int row = row0 + ai * HALF + m * 16; float sq = 0.f;
; #pragma unroll
;                 for (int bj = 0; bj < 2; ++bj) {
;                     const size_t off = (size_t)row * DM + col0 + bj * HALF;
;                     const f32x4 b0 = *(const f32x4*)(base + off), b1 = *(const f32x4*)(base + off + 4);
;                     const f32x4 x0 = b0 + acc[ai][bj][m][0] * alpha, x1 = b1 + acc[ai][bj][m][1] * alpha;
;                     __builtin_nontemporal_store(x0, (f32x4*)(out + off)); __builtin_nontemporal_store(x1, (f32x4*)(out + off + 4));
;                     sq += (x0[0] * x0[0] + x0[1] * x0[1]) + (x0[2] * x0[2] + x0[3] * x0[3]) + (x1[0] * x1[0] + x1[1] * x1[1]) + (x1[2] * x1[2] + x1[3] * x1[3]);
;                     if (xb) { u32x4 w; w.x = cvt_pk_bf16(x0[0], x0[1]); w.y = cvt_pk_bf16(x0[2], x0[3]); w.z = cvt_pk_bf16(x1[0], x1[1]); w.w = cvt_pk_bf16(x1[2], x1[3]); *(u32x4*)(xb + off) = w; }
;                 }
;                 sq += __shfl_xor(sq, 16); sq += __shfl_xor(sq, 32);
;                 if (fq == 0) unsafeAtomicAdd(ss + row, sq);
;             }
	v_fma_f32 v60, v60, 1.0, v200
	v_fma_f32 v61, v61, 1.0, v201
	v_fma_f32 v62, v62, 1.0, v202
	v_fma_f32 v63, v63, 1.0, v203
	v_fma_f32 v56, v56, 1.0, v204
	v_fma_f32 v57, v57, 1.0, v205
	v_fma_f32 v58, v58, 1.0, v206
	v_fma_f32 v59, v59, 1.0, v207
	v_fma_f32 v52, v52, 1.0, v208
	v_fma_f32 v53, v53, 1.0, v209
	v_fma_f32 v54, v54, 1.0, v210
	v_fma_f32 v55, v55, 1.0, v211
	v_fma_f32 v48, v48, 1.0, v212
	v_fma_f32 v49, v49, 1.0, v213
	v_fma_f32 v50, v50, 1.0, v214
	v_fma_f32 v51, v51, 1.0, v215
	s_add_u32 s84, s82, 0xa0000
	s_addc_u32 s85, s83, 0
	global_load_dwordx4 v[184:187], v144, s[84:85]
	global_load_dwordx4 v[188:191], v144, s[84:85] offset:16
	global_load_dwordx4 v[192:195], v144, s[84:85] offset:512
	global_load_dwordx4 v[196:199], v144, s[84:85] offset:528
	s_add_u32 s86, s82, 0x80000
	s_addc_u32 s87, s83, 0
	global_store_dwordx4 v144, v[60:63], s[86:87] nt
	global_store_dwordx4 v144, v[56:59], s[86:87] offset:16 nt
	global_store_dwordx4 v144, v[52:55], s[86:87] offset:512 nt
	global_store_dwordx4 v144, v[48:51], s[86:87] offset:528 nt
	v_cvt_pk_bf16_f32 v236, v60, v61
	v_cvt_pk_bf16_f32 v237, v62, v63
	v_cvt_pk_bf16_f32 v238, v56, v57
	v_cvt_pk_bf16_f32 v239, v58, v59
	v_cvt_pk_bf16_f32 v240, v52, v53
	v_cvt_pk_bf16_f32 v241, v54, v55
	v_cvt_pk_bf16_f32 v242, v48, v49
	v_cvt_pk_bf16_f32 v243, v50, v51
	s_add_u32 s88, s72, 0x40000
	s_addc_u32 s89, s73, 0
	global_store_dwordx4 v145, v[236:239], s[88:89]
	global_store_dwordx4 v145, v[240:243], s[88:89] offset:256
	v_mul_f32_e32 v232, v61, v61
	v_fmac_f32_e32 v232, v60, v60
	v_mul_f32_e32 v233, v57, v57
	v_fmac_f32_e32 v233, v56, v56
	v_mul_f32_e32 v234, v53, v53
	v_fmac_f32_e32 v234, v52, v52
	v_mul_f32_e32 v235, v49, v49
	v_fmac_f32_e32 v235, v48, v48
	v_mul_f32_e32 v248, v63, v63
	v_fmac_f32_e32 v248, v62, v62
	v_mul_f32_e32 v249, v59, v59
	v_fmac_f32_e32 v249, v58, v58
	v_mul_f32_e32 v250, v55, v55
	v_fmac_f32_e32 v250, v54, v54
	v_mul_f32_e32 v251, v51, v51
	v_fmac_f32_e32 v251, v50, v50
	v_add_f32_e32 v232, v232, v248
	v_add_f32_e32 v233, v233, v249
	v_add_f32_e32 v234, v234, v250
	v_add_f32_e32 v235, v235, v251
	v_add_f32_e32 v232, v232, v233
	v_add_f32_e32 v234, v234, v235
	v_add_f32_e32 v232, v232, v234
	ds_bpermute_b32 v233, v147, v232
	s_waitcnt lgkmcnt(0)
	v_add_f32_e32 v232, v232, v233
	ds_bpermute_b32 v233, v148, v232
	s_waitcnt lgkmcnt(0)
	v_add_f32_e32 v232, v232, v233
	s_and_saveexec_b64 s[6:7], s[8:9]
	s_nop 1
	global_atomic_add_f32 v146, v232, s[2:3] offset:512
	s_mov_b64 exec, s[6:7]
	s_waitcnt vmcnt(18)
	v_fma_f32 v44, v44, 1.0, v216
	v_fma_f32 v45, v45, 1.0, v217
	v_fma_f32 v46, v46, 1.0, v218
	v_fma_f32 v47, v47, 1.0, v219
	v_fma_f32 v40, v40, 1.0, v220
	v_fma_f32 v41, v41, 1.0, v221
	v_fma_f32 v42, v42, 1.0, v222
	v_fma_f32 v43, v43, 1.0, v223
	v_fma_f32 v36, v36, 1.0, v224
	v_fma_f32 v37, v37, 1.0, v225
	v_fma_f32 v38, v38, 1.0, v226
	v_fma_f32 v39, v39, 1.0, v227
	v_fma_f32 v32, v32, 1.0, v228
	v_fma_f32 v33, v33, 1.0, v229
	v_fma_f32 v34, v34, 1.0, v230
	v_fma_f32 v35, v35, 1.0, v231
	s_add_u32 s84, s82, 0xb0000
	s_addc_u32 s85, s83, 0
	global_load_dwordx4 v[200:203], v144, s[84:85]
	global_load_dwordx4 v[204:207], v144, s[84:85] offset:16
	global_load_dwordx4 v[208:211], v144, s[84:85] offset:512
	global_load_dwordx4 v[212:215], v144, s[84:85] offset:528
	s_add_u32 s86, s82, 0x90000
	s_addc_u32 s87, s83, 0
	global_store_dwordx4 v144, v[44:47], s[86:87] nt
	global_store_dwordx4 v144, v[40:43], s[86:87] offset:16 nt
	global_store_dwordx4 v144, v[36:39], s[86:87] offset:512 nt
	global_store_dwordx4 v144, v[32:35], s[86:87] offset:528 nt
	v_cvt_pk_bf16_f32 v236, v44, v45
	v_cvt_pk_bf16_f32 v237, v46, v47
	v_cvt_pk_bf16_f32 v238, v40, v41
	v_cvt_pk_bf16_f32 v239, v42, v43
	v_cvt_pk_bf16_f32 v240, v36, v37
	v_cvt_pk_bf16_f32 v241, v38, v39
	v_cvt_pk_bf16_f32 v242, v32, v33
	v_cvt_pk_bf16_f32 v243, v34, v35
	s_add_u32 s88, s72, 0x48000
	s_addc_u32 s89, s73, 0
	global_store_dwordx4 v145, v[236:239], s[88:89]
	global_store_dwordx4 v145, v[240:243], s[88:89] offset:256
	v_mul_f32_e32 v232, v45, v45
	v_fmac_f32_e32 v232, v44, v44
	v_mul_f32_e32 v233, v41, v41
	v_fmac_f32_e32 v233, v40, v40
	v_mul_f32_e32 v234, v37, v37
	v_fmac_f32_e32 v234, v36, v36
	v_mul_f32_e32 v235, v33, v33
	v_fmac_f32_e32 v235, v32, v32
	v_mul_f32_e32 v248, v47, v47
	v_fmac_f32_e32 v248, v46, v46
	v_mul_f32_e32 v249, v43, v43
	v_fmac_f32_e32 v249, v42, v42
	v_mul_f32_e32 v250, v39, v39
	v_fmac_f32_e32 v250, v38, v38
	v_mul_f32_e32 v251, v35, v35
	v_fmac_f32_e32 v251, v34, v34
	v_add_f32_e32 v232, v232, v248
	v_add_f32_e32 v233, v233, v249
	v_add_f32_e32 v234, v234, v250
	v_add_f32_e32 v235, v235, v251
	v_add_f32_e32 v232, v232, v233
	v_add_f32_e32 v234, v234, v235
	v_add_f32_e32 v232, v232, v234
	ds_bpermute_b32 v233, v147, v232
	s_waitcnt lgkmcnt(0)
; __device__ __forceinline__ unsigned cvt_pk_bf16(float lo, float hi) { f32x2_t v = {lo, hi}; bf16x2_t b = __builtin_convertvector(v, bf16x2_t); return __builtin_bit_cast(unsigned, b); }
;     __device__ __forceinline__ void operator()(const Acc& acc, const Unit& u, int wr, int wc, int fr, int fq) const {
;         const int row0 = u.pm * BM + wr * 64 + fr, col0 = u.pn * BM + wc * 32 + 8 * fq;
; #pragma unroll
;         for (int ai = 0; ai < 2; ++ai)
; #pragma unroll
;             for (int m = 0; m < 4; ++m) {
;                 const int row = row0 + ai * HALF + m * 16; float sq = 0.f;
; #pragma unroll
;                 for (int bj = 0; bj < 2; ++bj) {
;                     const size_t off = (size_t)row * DM + col0 + bj * HALF;
;                     const f32x4 b0 = *(const f32x4*)(base + off), b1 = *(const f32x4*)(base + off + 4);
;                     const f32x4 x0 = b0 + acc[ai][bj][m][0] * alpha, x1 = b1 + acc[ai][bj][m][1] * alpha;
;                     __builtin_nontemporal_store(x0, (f32x4*)(out + off)); __builtin_nontemporal_store(x1, (f32x4*)(out + off + 4));
;                     sq += (x0[0] * x0[0] + x0[1] * x0[1]) + (x0[2] * x0[2] + x0[3] * x0[3]) + (x1[0] * x1[0] + x1[1] * x1[1]) + (x1[2] * x1[2] + x1[3] * x1[3]);
;                     if (xb) { u32x4 w; w.x = cvt_pk_bf16(x0[0], x0[1]); w.y = cvt_pk_bf16(x0[2], x0[3]); w.z = cvt_pk_bf16(x1[0], x1[1]); w.w = cvt_pk_bf16(x1[2], x1[3]); *(u32x4*)(xb + off) = w; }
;                 }
;                 sq += __shfl_xor(sq, 16); sq += __shfl_xor(sq, 32);
;                 if (fq == 0) unsafeAtomicAdd(ss + row, sq);
;             }
	v_add_f32_e32 v232, v232, v233
	ds_bpermute_b32 v233, v148, v232
	s_waitcnt lgkmcnt(0)
	v_add_f32_e32 v232, v232, v233
	s_and_saveexec_b64 s[6:7], s[8:9]
	s_nop 1
	global_atomic_add_f32 v146, v232, s[2:3] offset:576
	s_mov_b64 exec, s[6:7]
	s_waitcnt vmcnt(18)
	v_fma_f32 v28, v28, 1.0, v184
	v_fma_f32 v29, v29, 1.0, v185
	v_fma_f32 v30, v30, 1.0, v186
	v_fma_f32 v31, v31, 1.0, v187
	v_fma_f32 v24, v24, 1.0, v188
	v_fma_f32 v25, v25, 1.0, v189
	v_fma_f32 v26, v26, 1.0, v190
	v_fma_f32 v27, v27, 1.0, v191
	v_fma_f32 v20, v20, 1.0, v192
	v_fma_f32 v21, v21, 1.0, v193
	v_fma_f32 v22, v22, 1.0, v194
	v_fma_f32 v23, v23, 1.0, v195
	v_fma_f32 v16, v16, 1.0, v196
	v_fma_f32 v17, v17, 1.0, v197
	v_fma_f32 v18, v18, 1.0, v198
	v_fma_f32 v19, v19, 1.0, v199
	s_add_u32 s86, s82, 0xa0000
	s_addc_u32 s87, s83, 0
	global_store_dwordx4 v144, v[28:31], s[86:87] nt
	global_store_dwordx4 v144, v[24:27], s[86:87] offset:16 nt
	global_store_dwordx4 v144, v[20:23], s[86:87] offset:512 nt
	global_store_dwordx4 v144, v[16:19], s[86:87] offset:528 nt
	v_cvt_pk_bf16_f32 v236, v28, v29
	v_cvt_pk_bf16_f32 v237, v30, v31
	v_cvt_pk_bf16_f32 v238, v24, v25
	v_cvt_pk_bf16_f32 v239, v26, v27
	v_cvt_pk_bf16_f32 v240, v20, v21
	v_cvt_pk_bf16_f32 v241, v22, v23
	v_cvt_pk_bf16_f32 v242, v16, v17
	v_cvt_pk_bf16_f32 v243, v18, v19
	s_add_u32 s88, s72, 0x50000
	s_addc_u32 s89, s73, 0
	global_store_dwordx4 v145, v[236:239], s[88:89]
	global_store_dwordx4 v145, v[240:243], s[88:89] offset:256
	v_mul_f32_e32 v232, v29, v29
	v_fmac_f32_e32 v232, v28, v28
	v_mul_f32_e32 v233, v25, v25
	v_fmac_f32_e32 v233, v24, v24
	v_mul_f32_e32 v234, v21, v21
	v_fmac_f32_e32 v234, v20, v20
	v_mul_f32_e32 v235, v17, v17
	v_fmac_f32_e32 v235, v16, v16
	v_mul_f32_e32 v248, v31, v31
	v_fmac_f32_e32 v248, v30, v30
	v_mul_f32_e32 v249, v27, v27
	v_fmac_f32_e32 v249, v26, v26
	v_mul_f32_e32 v250, v23, v23
	v_fmac_f32_e32 v250, v22, v22
	v_mul_f32_e32 v251, v19, v19
	v_fmac_f32_e32 v251, v18, v18
	v_add_f32_e32 v232, v232, v248
	v_add_f32_e32 v233, v233, v249
	v_add_f32_e32 v234, v234, v250
	v_add_f32_e32 v235, v235, v251
	v_add_f32_e32 v232, v232, v233
	v_add_f32_e32 v234, v234, v235
	v_add_f32_e32 v232, v232, v234
	ds_bpermute_b32 v233, v147, v232
	s_waitcnt lgkmcnt(0)
	v_add_f32_e32 v232, v232, v233
	ds_bpermute_b32 v233, v148, v232
	s_waitcnt lgkmcnt(0)
	v_add_f32_e32 v232, v232, v233
	s_and_saveexec_b64 s[6:7], s[8:9]
	s_nop 1
	global_atomic_add_f32 v146, v232, s[2:3] offset:640
	s_mov_b64 exec, s[6:7]
	s_waitcnt vmcnt(14)
	v_fma_f32 v12, v12, 1.0, v200
	v_fma_f32 v13, v13, 1.0, v201
	v_fma_f32 v14, v14, 1.0, v202
	v_fma_f32 v15, v15, 1.0, v203
	v_fma_f32 v8, v8, 1.0, v204
	v_fma_f32 v9, v9, 1.0, v205
	v_fma_f32 v10, v10, 1.0, v206
	v_fma_f32 v11, v11, 1.0, v207
	v_fma_f32 v4, v4, 1.0, v208
	v_fma_f32 v5, v5, 1.0, v209
	v_fma_f32 v6, v6, 1.0, v210
	v_fma_f32 v7, v7, 1.0, v211
	v_fma_f32 v0, v0, 1.0, v212
	v_fma_f32 v1, v1, 1.0, v213
	v_fma_f32 v2, v2, 1.0, v214
	v_fma_f32 v3, v3, 1.0, v215
	s_add_u32 s86, s82, 0xb0000
	s_addc_u32 s87, s83, 0
	global_store_dwordx4 v144, v[12:15], s[86:87] nt
	global_store_dwordx4 v144, v[8:11], s[86:87] offset:16 nt
	global_store_dwordx4 v144, v[4:7], s[86:87] offset:512 nt
	global_store_dwordx4 v144, v[0:3], s[86:87] offset:528 nt
	v_cvt_pk_bf16_f32 v236, v12, v13
	v_cvt_pk_bf16_f32 v237, v14, v15
	v_cvt_pk_bf16_f32 v238, v8, v9
	v_cvt_pk_bf16_f32 v239, v10, v11
	v_cvt_pk_bf16_f32 v240, v4, v5
	v_cvt_pk_bf16_f32 v241, v6, v7
	v_cvt_pk_bf16_f32 v242, v0, v1
	v_cvt_pk_bf16_f32 v243, v2, v3
	s_add_u32 s88, s72, 0x58000
	s_addc_u32 s89, s73, 0
	global_store_dwordx4 v145, v[236:239], s[88:89]
	global_store_dwordx4 v145, v[240:243], s[88:89] offset:256
	v_mul_f32_e32 v232, v13, v13
	v_fmac_f32_e32 v232, v12, v12
	v_mul_f32_e32 v233, v9, v9
	v_fmac_f32_e32 v233, v8, v8
	v_mul_f32_e32 v234, v5, v5
	v_fmac_f32_e32 v234, v4, v4
	v_mul_f32_e32 v235, v1, v1
	v_fmac_f32_e32 v235, v0, v0
	v_mul_f32_e32 v248, v15, v15
	v_fmac_f32_e32 v248, v14, v14
	v_mul_f32_e32 v249, v11, v11
	v_fmac_f32_e32 v249, v10, v10
	v_mul_f32_e32 v250, v7, v7
	v_fmac_f32_e32 v250, v6, v6
	v_mul_f32_e32 v251, v3, v3
	v_fmac_f32_e32 v251, v2, v2
	v_add_f32_e32 v232, v232, v248
	v_add_f32_e32 v233, v233, v249
	v_add_f32_e32 v234, v234, v250
	v_add_f32_e32 v235, v235, v251
	v_add_f32_e32 v232, v232, v233
	v_add_f32_e32 v234, v234, v235
	v_add_f32_e32 v232, v232, v234
	ds_bpermute_b32 v233, v147, v232
	s_waitcnt lgkmcnt(0)
	v_add_f32_e32 v232, v232, v233
	ds_bpermute_b32 v233, v148, v232
	s_waitcnt lgkmcnt(0)
	v_add_f32_e32 v232, v232, v233
	s_and_saveexec_b64 s[6:7], s[8:9]
	s_nop 1
	global_atomic_add_f32 v146, v232, s[2:3] offset:704
	s_mov_b64 exec, s[6:7]
	s_branch .Lg6_epi_done
